# loop-edge edit: fragment-address VALU of the next k-step hoisted ahead of the wait+barrier in all six GEMM k-loops, so ds_reads issue right at barrier release
# speedup vs baseline: 1.0428x; 1.0079x over previous
; #define G_TILE(kt_, st_) do { const size_t ko_ = (size_t)(kt_) * 1024; unsigned char* d_ = smem + (st_) * 16384; \
;         _Pragma("unroll") for (int s_ = 0; s_ < 8; ++s_) GLDS16(Abase + (size_t)s_ * ksub + ko_ + voff, d_ + s_ * 1024); \
;         _Pragma("unroll") for (int s_ = 0; s_ < 8; ++s_) GLDS16(Bbase + (size_t)s_ * ksub + ko_ + voff, d_ + 8192 + s_ * 1024); } while (0)
; template <int EPI>
; __device__ __forceinline__ void gemm_tile(const Params& p, int l, const u16* __restrict__ A, int lda, const u16* __restrict__ Bt, int K, int m0, int n0, unsigned char* smem) {
;     ...
;     f32x4 acc[4][4];
; #pragma unroll
;     for (int i = 0; i < 4; ++i)
; #pragma unroll
;         for (int j = 0; j < 4; ++j) acc[i][j] = (f32x4){0.f, 0.f, 0.f, 0.f};
;     const unsigned voff = (unsigned)(lane * 16);
;     const size_t ksub = (size_t)(K >> 5) * 1024;
;     const unsigned char* Abase = (const unsigned char*)A + (size_t)(m0 >> 4) * ksub;
;     const unsigned char* Bbase = (const unsigned char*)Bt + (size_t)(n0 >> 4) * ksub;
;     (void)lda;
;     ...
;     const int nk = K >> 5;
;     G_TILE(wid, wid);
;     const unsigned char* fa = smem + (wr * 4) * 1024 + fr * 64 + fq * 16;
;     const unsigned char* fb = smem + 8192 + (wc * 4) * 1024 + fr * 64 + fq * 16;
;     int st = 0, stn = 4;
;     if (wid == 0) asm volatile("s_waitcnt vmcnt(0)" ::: "memory");
;     __builtin_amdgcn_s_barrier();
;     asm volatile("" ::: "memory");
.Loin_pro:
	s_add_i32 s1, s23, s37
	s_mov_b32 m0, s1
	s_add_i32 s1, s1, 0x400
	global_load_lds_dwordx4 v252, s[30:31]
	s_mov_b32 m0, s1
	s_add_i32 s1, s23, s38
	global_load_lds_dwordx4 v253, s[30:31]
	s_mov_b32 m0, s1
	s_add_i32 s1, s1, 0x400
	global_load_lds_dwordx4 v252, s[28:29]
	s_mov_b32 m0, s1
	s_add_u32 s30, s30, 0x400
	global_load_lds_dwordx4 v253, s[28:29]
	s_addc_u32 s31, s31, 0
	s_add_u32 s28, s28, 0x400
	s_addc_u32 s29, s29, 0
	s_add_i32 s23, s23, 0x4000
	s_cmp_lg_u32 s23, 0x10000
	s_cbranch_scc1 .Loin_pro
	v_ashrrev_i32_e32 v73, 7, v136
	v_and_b32_e32 v72, 15, v136
	v_and_b32_e32 v67, 1, v66
	v_lshlrev_b32_e32 v2, 12, v73
	v_lshlrev_b32_e32 v3, 6, v72
	v_and_b32_e32 v4, 48, v136
	v_and_b32_e32 v5, 8, v136
	v_lshlrev_b32_e32 v5, 2, v5
	v_xor_b32_e32 v4, v4, v5
	v_add3_u32 v75, v2, v3, v4
	v_lshlrev_b32_e32 v2, 12, v67
	v_add3_u32 v74, v2, v3, v4
	s_waitcnt lgkmcnt(0)
	v_mov_b32_e32 v2, 0
	v_mov_b32_e32 v3, v2
	v_mov_b32_e32 v4, v2
	v_mov_b32_e32 v5, v2
	v_mov_b32_e32 v6, v2
	v_mov_b32_e32 v7, v2
	v_mov_b32_e32 v8, v2
	v_mov_b32_e32 v9, v2
	v_mov_b32_e32 v10, v2
	v_mov_b32_e32 v11, v2
	v_mov_b32_e32 v12, v2
	v_mov_b32_e32 v13, v2
	v_mov_b32_e32 v14, v2
	v_mov_b32_e32 v15, v2
	v_mov_b32_e32 v16, v2
	v_mov_b32_e32 v17, v2
	v_mov_b32_e32 v18, v2
	v_mov_b32_e32 v19, v2
	v_mov_b32_e32 v20, v2
	v_mov_b32_e32 v21, v2
	v_mov_b32_e32 v22, v2
	v_mov_b32_e32 v23, v2
	v_mov_b32_e32 v24, v2
	v_mov_b32_e32 v25, v2
	v_mov_b32_e32 v26, v2
	v_mov_b32_e32 v27, v2
	v_mov_b32_e32 v28, v2
	v_mov_b32_e32 v29, v2
	v_mov_b32_e32 v30, v2
	v_mov_b32_e32 v31, v2
	v_mov_b32_e32 v32, v2
	v_mov_b32_e32 v33, v2
	v_mov_b32_e32 v34, v2
	v_mov_b32_e32 v35, v2
	v_mov_b32_e32 v36, v2
	v_mov_b32_e32 v37, v2
	v_mov_b32_e32 v38, v2
	v_mov_b32_e32 v39, v2
	v_mov_b32_e32 v40, v2
	v_mov_b32_e32 v41, v2
	v_mov_b32_e32 v42, v2
	v_mov_b32_e32 v43, v2
	v_mov_b32_e32 v44, v2
	v_mov_b32_e32 v45, v2
	v_mov_b32_e32 v46, v2
	v_mov_b32_e32 v47, v2
	v_mov_b32_e32 v48, v2
	v_mov_b32_e32 v49, v2
	v_mov_b32_e32 v50, v2
	v_mov_b32_e32 v51, v2
	v_mov_b32_e32 v52, v2
	v_mov_b32_e32 v53, v2
	v_mov_b32_e32 v54, v2
	v_mov_b32_e32 v55, v2
	v_mov_b32_e32 v56, v2
	v_mov_b32_e32 v57, v2
	v_mov_b32_e32 v58, v2
	v_mov_b32_e32 v59, v2
	v_mov_b32_e32 v60, v2
	v_mov_b32_e32 v61, v2
	v_mov_b32_e32 v62, v2
	v_mov_b32_e32 v63, v2
	v_mov_b32_e32 v64, v2
	v_mov_b32_e32 v65, v2
	s_mov_b64 s[46:47], 0x6adc100
	s_mov_b64 s[18:19], 0x6ae4100
	s_mov_b64 s[44:45], 0x6aec100
	s_mov_b32 s36, 0
	s_mov_b32 s0, 0
	v_add_u32_e32 v88, s0, v75
	v_add_u32_e32 v104, s0, v74
	s_branch .Loin_head

; #define G_TILE(kt_, st_) do { const size_t ko_ = (size_t)(kt_) * 1024; unsigned char* d_ = smem + (st_) * 16384; \
;         _Pragma("unroll") for (int s_ = 0; s_ < 8; ++s_) GLDS16(Abase + (size_t)s_ * ksub + ko_ + voff, d_ + s_ * 1024); \
;         _Pragma("unroll") for (int s_ = 0; s_ < 8; ++s_) GLDS16(Bbase + (size_t)s_ * ksub + ko_ + voff, d_ + 8192 + s_ * 1024); } while (0)
; template <int EPI>
; __device__ __forceinline__ void gemm_tile(const Params& p, int l, const u16* __restrict__ A, int lda, const u16* __restrict__ Bt, int K, int m0, int n0, unsigned char* smem) {
;     ...
;     for (int kt = 0; kt < nk; ++kt) {
;         if (((kt + 1) & 3) == wid && kt + 1 < nk) asm volatile("s_waitcnt vmcnt(0)" ::: "memory");
;         __builtin_amdgcn_s_barrier();
;         asm volatile("" ::: "memory");
;         if ((kt & 3) == wid && kt + 4 < nk) G_TILE(kt + 4, stn);
;         const int so = st * 16384;
;         bf16x8 af[4], bv[4];
; #pragma unroll
;         for (int i = 0; i < 4; ++i) af[i] = *(const bf16x8*)(fa + so + i * 1024);
; #pragma unroll
;         for (int j = 0; j < 4; ++j) bv[j] = *(const bf16x8*)(fb + so + j * 1024);
;         __builtin_amdgcn_s_setprio(1);
; #pragma unroll
;         for (int i = 0; i < 4; ++i)
; #pragma unroll
;             for (int j = 0; j < 4; ++j) acc[i][j] = __builtin_amdgcn_mfma_f32_16x16x32_bf16(af[i], bv[j], acc[i][j], 0, 0, 0);
;         __builtin_amdgcn_s_setprio(0);
;         st = (st == 4) ? 0 : st + 1;
;         stn = (stn == 4) ? 0 : stn + 1;
.Loin_bar:
	s_barrier
	ds_read_b128 v[92:95], v104 offset:8192
	ds_read_b128 v[96:99], v104 offset:9216
	ds_read_b128 v[100:103], v104 offset:10240
	ds_read_b128 v[104:107], v104 offset:11264
	ds_read_b128 v[76:79], v88
	ds_read_b128 v[80:83], v88 offset:1024
	ds_read_b128 v[84:87], v88 offset:2048
	ds_read_b128 v[88:91], v88 offset:3072
	s_cmp_lt_u32 s36, 28
	s_cbranch_scc0 .Loin_mm
	s_add_i32 s1, s23, s37
	s_mov_b32 m0, s1
	s_add_i32 s1, s1, 0x400
	global_load_lds_dwordx4 v252, s[30:31]
	s_mov_b32 m0, s1
	s_add_i32 s1, s23, s38
	global_load_lds_dwordx4 v253, s[30:31]
	s_mov_b32 m0, s1
	s_add_i32 s1, s1, 0x400
	global_load_lds_dwordx4 v252, s[28:29]
	s_mov_b32 m0, s1
	s_add_u32 s30, s30, 0x400
	global_load_lds_dwordx4 v253, s[28:29]
	s_addc_u32 s31, s31, 0
	s_add_u32 s28, s28, 0x400
	s_addc_u32 s29, s29, 0
	s_add_i32 s23, s23, 0x4000
	s_cmp_eq_u32 s23, 0x14000
	s_cselect_b32 s23, 0, s23
.Loin_mm:
	s_setprio 1
	s_waitcnt lgkmcnt(3)
	v_mfma_f32_16x16x32_bf16 v[62:65], v[76:79], v[92:95], v[62:65]
	v_mfma_f32_16x16x32_bf16 v[58:61], v[76:79], v[96:99], v[58:61]
	v_mfma_f32_16x16x32_bf16 v[54:57], v[76:79], v[100:103], v[54:57]
	v_mfma_f32_16x16x32_bf16 v[50:53], v[76:79], v[104:107], v[50:53]
	s_waitcnt lgkmcnt(2)
	v_mfma_f32_16x16x32_bf16 v[46:49], v[80:83], v[92:95], v[46:49]
	v_mfma_f32_16x16x32_bf16 v[42:45], v[80:83], v[96:99], v[42:45]
	v_mfma_f32_16x16x32_bf16 v[38:41], v[80:83], v[100:103], v[38:41]
	v_mfma_f32_16x16x32_bf16 v[34:37], v[80:83], v[104:107], v[34:37]
	s_waitcnt lgkmcnt(1)
	v_mfma_f32_16x16x32_bf16 v[30:33], v[84:87], v[92:95], v[30:33]
	v_mfma_f32_16x16x32_bf16 v[26:29], v[84:87], v[96:99], v[26:29]
	v_mfma_f32_16x16x32_bf16 v[22:25], v[84:87], v[100:103], v[22:25]
	v_mfma_f32_16x16x32_bf16 v[18:21], v[84:87], v[104:107], v[18:21]
	s_waitcnt lgkmcnt(0)
	v_mfma_f32_16x16x32_bf16 v[14:17], v[88:91], v[92:95], v[14:17]
	v_mfma_f32_16x16x32_bf16 v[10:13], v[88:91], v[96:99], v[10:13]
	v_mfma_f32_16x16x32_bf16 v[6:9], v[88:91], v[100:103], v[6:9]
	v_mfma_f32_16x16x32_bf16 v[2:5], v[88:91], v[104:107], v[2:5]
	s_setprio 0
	s_add_i32 s0, s0, 0x4000
	s_cmp_eq_u32 s0, 0x14000
	s_cselect_b32 s0, 0, s0
	v_add_u32_e32 v88, s0, v75
	v_add_u32_e32 v104, s0, v74
	s_add_i32 s36, s36, 1
	s_cmp_lg_u32 s36, 31
	s_cbranch_scc1 .Loin_head
	s_branch .LBB0_277

; __device__ __forceinline__ int opaque_tid() { int t = threadIdx.x; asm volatile("" : "+v"(t)); return t; }
; #define G3_TILE(kt_, st_) do { const size_t ko_ = (size_t)(kt_) * 1024; unsigned char* d_ = smem + (st_) * 20480; \
;         _Pragma("unroll") for (int s_ = 0; s_ < 12; ++s_) GLDS16(Abase + (size_t)s_ * ksub + ko_ + voff, d_ + s_ * 1024); \
;         _Pragma("unroll") for (int s_ = 0; s_ < 8; ++s_) GLDS16(Bbase + (size_t)s_ * ksub + ko_ + voff, d_ + 12288 + s_ * 1024); } while (0)
; template <int EPI>
; __device__ __forceinline__ void gemm_tile3(const Params& p, int l, const u16* __restrict__ A, int lda, const u16* __restrict__ Bt, int K, int m0, int n0, unsigned char* smem) {
;     const int tid = opaque_tid(), lane = tid & 63, wid = tid >> 6, wr = wid >> 1, wc = wid & 1, fr = lane & 15, fq = lane >> 4;
;     f32x4 acc[6][4];
; #pragma unroll
;     for (int i = 0; i < 6; ++i)
; #pragma unroll
;         for (int j = 0; j < 4; ++j) acc[i][j] = (f32x4){0.f, 0.f, 0.f, 0.f};
;     const unsigned voff = (unsigned)(lane * 16);
;     const size_t ksub = (size_t)(K >> 5) * 1024;
;     const unsigned char* Abase = (const unsigned char*)A + (size_t)(m0 >> 4) * ksub;
;     const unsigned char* Bbase = (const unsigned char*)Bt + (size_t)(n0 >> 4) * ksub;
;     (void)lda;
;     ...
;     const int nk = K >> 5;
;     if (wid < 3) G3_TILE(wid, wid);
;     const unsigned char* fa = smem + (wr * 6) * 1024 + fr * 64 + fq * 16;
;     const unsigned char* fb = smem + 12288 + (wc * 4) * 1024 + fr * 64 + fq * 16;
;     int st = 0, stn = 3;
;     if (wid == 0) asm volatile("s_waitcnt vmcnt(0)" ::: "memory");
;     asm volatile("s_waitcnt lgkmcnt(0)" ::: "memory");
;     __builtin_amdgcn_s_barrier();
;     asm volatile("" ::: "memory");
.LoA_pro:
	s_add_i32 s17, s16, s54
	s_add_i32 s18, s16, s55
	s_mov_b32 m0, s17
	s_add_i32 s17, s17, 0x400
	global_load_lds_dwordx4 v252, s[28:29]
	s_mov_b32 m0, s17
	s_add_i32 s17, s17, 0x400
	global_load_lds_dwordx4 v253, s[28:29]
	s_mov_b32 m0, s17
	s_nop 0
	global_load_lds_dwordx4 v254, s[28:29]
	s_mov_b32 m0, s18
	s_add_i32 s18, s18, 0x400
	global_load_lds_dwordx4 v252, s[30:31]
	s_mov_b32 m0, s18
	s_add_u32 s28, s28, 0x400
	global_load_lds_dwordx4 v253, s[30:31]
	s_addc_u32 s29, s29, 0
	s_add_u32 s30, s30, 0x400
	s_addc_u32 s31, s31, 0
	s_add_i32 s16, s16, 0x5000
	s_cmp_lg_u32 s16, 0xf000
	s_cbranch_scc1 .LoA_pro
	v_ashrrev_i32_e32 v105, 7, v104
	s_movk_i32 s17, 0x1800
	v_and_b32_e32 v106, 15, v104
	v_mul_lo_u32 v2, v105, s17
	v_and_b32_e32 v99, 1, v98
	v_lshlrev_b32_e32 v3, 6, v106
	v_and_b32_e32 v4, 48, v104
	v_and_b32_e32 v5, 8, v104
	v_lshlrev_b32_e32 v5, 2, v5
	v_xor_b32_e32 v4, v4, v5
	v_add3_u32 v107, v2, v3, v4
	v_lshlrev_b32_e32 v2, 12, v99
	v_add3_u32 v108, v2, v3, v4
	s_waitcnt lgkmcnt(0)
	v_mov_b32_e32 v2, 0
	v_mov_b32_e32 v3, v2
	v_mov_b32_e32 v4, v2
	v_mov_b32_e32 v5, v2
	v_mov_b32_e32 v6, v2
	v_mov_b32_e32 v7, v2
	v_mov_b32_e32 v8, v2
	v_mov_b32_e32 v9, v2
	v_mov_b32_e32 v10, v2
	v_mov_b32_e32 v11, v2
	v_mov_b32_e32 v12, v2
	v_mov_b32_e32 v13, v2
	v_mov_b32_e32 v14, v2
	v_mov_b32_e32 v15, v2
	v_mov_b32_e32 v16, v2
	v_mov_b32_e32 v17, v2
	v_mov_b32_e32 v18, v2
	v_mov_b32_e32 v19, v2
	v_mov_b32_e32 v20, v2
	v_mov_b32_e32 v21, v2
	v_mov_b32_e32 v22, v2
	v_mov_b32_e32 v23, v2
	v_mov_b32_e32 v24, v2
	v_mov_b32_e32 v25, v2
	v_mov_b32_e32 v26, v2
	v_mov_b32_e32 v27, v2
	v_mov_b32_e32 v28, v2
	v_mov_b32_e32 v29, v2
	v_mov_b32_e32 v30, v2
	v_mov_b32_e32 v31, v2
	v_mov_b32_e32 v32, v2
	v_mov_b32_e32 v33, v2
	v_mov_b32_e32 v34, v2
	v_mov_b32_e32 v35, v2
	v_mov_b32_e32 v36, v2
	v_mov_b32_e32 v37, v2
	v_mov_b32_e32 v38, v2
	v_mov_b32_e32 v39, v2
	v_mov_b32_e32 v40, v2
	v_mov_b32_e32 v41, v2
	v_mov_b32_e32 v42, v2
	v_mov_b32_e32 v43, v2
	v_mov_b32_e32 v44, v2
	v_mov_b32_e32 v45, v2
	v_mov_b32_e32 v46, v2
	v_mov_b32_e32 v47, v2
	v_mov_b32_e32 v48, v2
	v_mov_b32_e32 v49, v2
	v_mov_b32_e32 v50, v2
	v_mov_b32_e32 v51, v2
	v_mov_b32_e32 v52, v2
	v_mov_b32_e32 v53, v2
	v_mov_b32_e32 v54, v2
	v_mov_b32_e32 v55, v2
	v_mov_b32_e32 v56, v2
	v_mov_b32_e32 v57, v2
	v_mov_b32_e32 v58, v2
	v_mov_b32_e32 v59, v2
	v_mov_b32_e32 v60, v2
	v_mov_b32_e32 v61, v2
	v_mov_b32_e32 v62, v2
	v_mov_b32_e32 v63, v2
	v_mov_b32_e32 v64, v2
	v_mov_b32_e32 v65, v2
	v_mov_b32_e32 v66, v2
	v_mov_b32_e32 v67, v2
	v_mov_b32_e32 v68, v2
	v_mov_b32_e32 v69, v2
	v_mov_b32_e32 v70, v2
	v_mov_b32_e32 v71, v2
	v_mov_b32_e32 v72, v2
	v_mov_b32_e32 v73, v2
	v_mov_b32_e32 v74, v2
	v_mov_b32_e32 v75, v2
	v_mov_b32_e32 v76, v2
	v_mov_b32_e32 v77, v2
	v_mov_b32_e32 v78, v2
	v_mov_b32_e32 v79, v2
	v_mov_b32_e32 v80, v2
	v_mov_b32_e32 v81, v2
	v_mov_b32_e32 v82, v2
	v_mov_b32_e32 v83, v2
	v_mov_b32_e32 v84, v2
	v_mov_b32_e32 v85, v2
	v_mov_b32_e32 v86, v2
	v_mov_b32_e32 v87, v2
	v_mov_b32_e32 v88, v2
	v_mov_b32_e32 v89, v2
	v_mov_b32_e32 v90, v2
	v_mov_b32_e32 v91, v2
	v_mov_b32_e32 v92, v2
	v_mov_b32_e32 v93, v2
	v_mov_b32_e32 v94, v2
	v_mov_b32_e32 v95, v2
	v_mov_b32_e32 v96, v2
	v_mov_b32_e32 v97, v2
	s_mov_b32 s37, 0
	s_mov_b32 s23, 0
	v_add_u32_e32 v109, s23, v108
	v_add_u32_e32 v0, s23, v107
	v_add_u32_e32 v109, 0x3000, v109
	s_branch .LoA_head

; template <int EPI>
; __device__ __forceinline__ void gemm_tile3(const Params& p, int l, const u16* __restrict__ A, int lda, const u16* __restrict__ Bt, int K, int m0, int n0, unsigned char* smem) {
;     ...
;     for (int kt = 0; kt < nk; ++kt) {
;         if (((kt + 1) & 3) == wid && kt + 1 < nk) asm volatile("s_waitcnt vmcnt(0)" ::: "memory");
;         __builtin_amdgcn_s_barrier();
;         asm volatile("" ::: "memory");
;         if (((kt + 3) & 3) == wid && kt + 3 < nk) G3_TILE(kt + 3, stn);
;         const int so = st * 20480;
;         bf16x8 af[6], bv[4];
;         {
;             typedef __attribute__((address_space(3))) unsigned char lds_u8;
;             const unsigned la = (unsigned)(uintptr_t)(lds_u8*)(fa + so);
;             const unsigned lb = (unsigned)(uintptr_t)(lds_u8*)(fb + so);
;     ...
;             DSR128(bv[0], lb, 0); DSR128(bv[1], lb, 1024); DSR128(bv[2], lb, 2048); DSR128(bv[3], lb, 3072);
;             DSR128(af[0], la, 0); DSR128(af[1], la, 1024); DSR128(af[2], la, 2048); DSR128(af[3], la, 3072); DSR128(af[4], la, 4096); DSR128(af[5], la, 5120);
;         }
;         __builtin_amdgcn_sched_barrier(0);
;         asm volatile("s_waitcnt lgkmcnt(5)" : "+v"(bv[0]), "+v"(bv[1]), "+v"(bv[2]), "+v"(bv[3]), "+v"(af[0]));
;         __builtin_amdgcn_sched_barrier(0);
; #pragma unroll
;         for (int j = 0; j < 4; ++j) acc[0][j] = __builtin_amdgcn_mfma_f32_16x16x32_bf16(bv[j], af[0], acc[0][j], 0, 0, 0);
;         __builtin_amdgcn_sched_barrier(0);
;         asm volatile("s_waitcnt lgkmcnt(4)" : "+v"(af[1]));
;         __builtin_amdgcn_sched_barrier(0);
; #pragma unroll
;         for (int j = 0; j < 4; ++j) acc[1][j] = __builtin_amdgcn_mfma_f32_16x16x32_bf16(bv[j], af[1], acc[1][j], 0, 0, 0);
;         __builtin_amdgcn_sched_barrier(0);
;         asm volatile("s_waitcnt lgkmcnt(3)" : "+v"(af[2]));
;         __builtin_amdgcn_sched_barrier(0);
; #pragma unroll
;         for (int j = 0; j < 4; ++j) acc[2][j] = __builtin_amdgcn_mfma_f32_16x16x32_bf16(bv[j], af[2], acc[2][j], 0, 0, 0);
;         __builtin_amdgcn_sched_barrier(0);
;         asm volatile("s_waitcnt lgkmcnt(2)" : "+v"(af[3]));
;         __builtin_amdgcn_sched_barrier(0);
; #pragma unroll
;         for (int j = 0; j < 4; ++j) acc[3][j] = __builtin_amdgcn_mfma_f32_16x16x32_bf16(bv[j], af[3], acc[3][j], 0, 0, 0);
;         __builtin_amdgcn_sched_barrier(0);
.LoA_bar:
	s_barrier
	ds_read_b128 v[110:113], v109 offset:0
	ds_read_b128 v[114:117], v109 offset:1024
	ds_read_b128 v[118:121], v109 offset:2048
	ds_read_b128 v[122:125], v109 offset:3072
	ds_read_b128 v[126:129], v0 offset:0
	ds_read_b128 v[130:133], v0 offset:1024
	ds_read_b128 v[134:137], v0 offset:2048
	ds_read_b128 v[138:141], v0 offset:3072
	ds_read_b128 v[142:145], v0 offset:4096
	ds_read_b128 v[146:149], v0 offset:5120
	s_cmp_lt_u32 s37, 29
	s_cbranch_scc0 .LoA_mm
	s_add_i32 s17, s16, s54
	s_add_i32 s18, s16, s55
	s_mov_b32 m0, s17
	s_add_i32 s17, s17, 0x400
	global_load_lds_dwordx4 v252, s[28:29]
	s_mov_b32 m0, s17
	s_add_i32 s17, s17, 0x400
	global_load_lds_dwordx4 v253, s[28:29]
	s_mov_b32 m0, s17
	s_nop 0
	global_load_lds_dwordx4 v254, s[28:29]
	s_mov_b32 m0, s18
	s_add_i32 s18, s18, 0x400
	global_load_lds_dwordx4 v252, s[30:31]
	s_mov_b32 m0, s18
	s_add_u32 s28, s28, 0x400
	global_load_lds_dwordx4 v253, s[30:31]
	s_addc_u32 s29, s29, 0
	s_add_u32 s30, s30, 0x400
	s_addc_u32 s31, s31, 0
	s_add_i32 s16, s16, 0x5000
	s_cmp_eq_u32 s16, 0x14000
	s_cselect_b32 s16, 0, s16
.LoA_mm:
	s_setprio 1
	s_waitcnt lgkmcnt(5)
	s_nop 0
	v_mfma_f32_16x16x32_bf16 v[94:97], v[110:113], v[126:129], v[94:97]
	v_mfma_f32_16x16x32_bf16 v[90:93], v[114:117], v[126:129], v[90:93]
	v_mfma_f32_16x16x32_bf16 v[86:89], v[118:121], v[126:129], v[86:89]
	v_mfma_f32_16x16x32_bf16 v[82:85], v[122:125], v[126:129], v[82:85]
	s_waitcnt lgkmcnt(4)
	s_nop 0
	v_mfma_f32_16x16x32_bf16 v[78:81], v[110:113], v[130:133], v[78:81]
	v_mfma_f32_16x16x32_bf16 v[74:77], v[114:117], v[130:133], v[74:77]
	v_mfma_f32_16x16x32_bf16 v[70:73], v[118:121], v[130:133], v[70:73]
	v_mfma_f32_16x16x32_bf16 v[66:69], v[122:125], v[130:133], v[66:69]
	s_waitcnt lgkmcnt(3)
	s_nop 0
	v_mfma_f32_16x16x32_bf16 v[62:65], v[110:113], v[134:137], v[62:65]
	v_mfma_f32_16x16x32_bf16 v[58:61], v[114:117], v[134:137], v[58:61]
	v_mfma_f32_16x16x32_bf16 v[54:57], v[118:121], v[134:137], v[54:57]
	v_mfma_f32_16x16x32_bf16 v[50:53], v[122:125], v[134:137], v[50:53]
	s_waitcnt lgkmcnt(2)
	s_nop 0
	v_mfma_f32_16x16x32_bf16 v[46:49], v[110:113], v[138:141], v[46:49]
	v_mfma_f32_16x16x32_bf16 v[42:45], v[114:117], v[138:141], v[42:45]
	v_mfma_f32_16x16x32_bf16 v[38:41], v[118:121], v[138:141], v[38:41]
	v_mfma_f32_16x16x32_bf16 v[34:37], v[122:125], v[138:141], v[34:37]
	s_waitcnt lgkmcnt(1)
	s_nop 0
	v_mfma_f32_16x16x32_bf16 v[30:33], v[110:113], v[142:145], v[30:33]
	v_mfma_f32_16x16x32_bf16 v[26:29], v[114:117], v[142:145], v[26:29]
	v_mfma_f32_16x16x32_bf16 v[22:25], v[118:121], v[142:145], v[22:25]
	v_mfma_f32_16x16x32_bf16 v[18:21], v[122:125], v[142:145], v[18:21]
	s_waitcnt lgkmcnt(0)
	s_add_i32 s23, s23, 0x5000
	s_add_i32 s37, s37, 1
	v_mfma_f32_16x16x32_bf16 v[14:17], v[110:113], v[146:149], v[14:17]
	s_cmp_eq_u32 s23, 0x14000
	s_cselect_b32 s23, 0, s23
	v_mfma_f32_16x16x32_bf16 v[10:13], v[114:117], v[146:149], v[10:13]
	s_cmp_lg_u32 s37, 32
	v_mfma_f32_16x16x32_bf16 v[6:9], v[118:121], v[146:149], v[6:9]
	v_mfma_f32_16x16x32_bf16 v[2:5], v[122:125], v[146:149], v[2:5]
	v_add_u32_e32 v109, s23, v108
	v_add_u32_e32 v0, s23, v107
	v_add_u32_e32 v109, 0x3000, v109
	s_setprio 0
	s_cbranch_scc1 .LoA_head
	s_branch .LBB0_451

; #define G_TILE(kt_, st_) do { const size_t ko_ = (size_t)(kt_) * 1024; unsigned char* d_ = smem + (st_) * 16384; \
;         _Pragma("unroll") for (int s_ = 0; s_ < 8; ++s_) GLDS16(Abase + (size_t)s_ * ksub + ko_ + voff, d_ + s_ * 1024); \
;         _Pragma("unroll") for (int s_ = 0; s_ < 8; ++s_) GLDS16(Bbase + (size_t)s_ * ksub + ko_ + voff, d_ + 8192 + s_ * 1024); } while (0)
; template <int EPI>
; __device__ __forceinline__ void gemm_tile(const Params& p, int l, const u16* __restrict__ A, int lda, const u16* __restrict__ Bt, int K, int m0, int n0, unsigned char* smem) {
;     ...
;     f32x4 acc[4][4];
; #pragma unroll
;     for (int i = 0; i < 4; ++i)
; #pragma unroll
;         for (int j = 0; j < 4; ++j) acc[i][j] = (f32x4){0.f, 0.f, 0.f, 0.f};
;     const unsigned voff = (unsigned)(lane * 16);
;     const size_t ksub = (size_t)(K >> 5) * 1024;
;     const unsigned char* Abase = (const unsigned char*)A + (size_t)(m0 >> 4) * ksub;
;     const unsigned char* Bbase = (const unsigned char*)Bt + (size_t)(n0 >> 4) * ksub;
;     (void)lda;
;     ...
;     const int nk = K >> 5;
;     G_TILE(wid, wid);
;     const unsigned char* fa = smem + (wr * 4) * 1024 + fr * 64 + fq * 16;
;     const unsigned char* fb = smem + 8192 + (wc * 4) * 1024 + fr * 64 + fq * 16;
;     int st = 0, stn = 4;
;     if (wid == 0) asm volatile("s_waitcnt vmcnt(0)" ::: "memory");
;     __builtin_amdgcn_s_barrier();
;     asm volatile("" ::: "memory");
.Lein_pro:
	s_add_i32 s1, s23, s37
	s_mov_b32 m0, s1
	s_add_i32 s1, s1, 0x400
	global_load_lds_dwordx4 v252, s[30:31]
	s_mov_b32 m0, s1
	s_add_i32 s1, s23, s38
	global_load_lds_dwordx4 v253, s[30:31]
	s_mov_b32 m0, s1
	s_add_i32 s1, s1, 0x400
	global_load_lds_dwordx4 v252, s[28:29]
	s_mov_b32 m0, s1
	s_add_u32 s30, s30, 0x400
	global_load_lds_dwordx4 v253, s[28:29]
	s_addc_u32 s31, s31, 0
	s_add_u32 s28, s28, 0x400
	s_addc_u32 s29, s29, 0
	s_add_i32 s23, s23, 0x4000
	s_cmp_lg_u32 s23, 0x10000
	s_cbranch_scc1 .Lein_pro
	v_ashrrev_i32_e32 v73, 7, v110
	v_and_b32_e32 v72, 15, v110
	v_and_b32_e32 v67, 1, v66
	v_lshlrev_b32_e32 v2, 12, v73
	v_lshlrev_b32_e32 v3, 6, v72
	v_and_b32_e32 v4, 48, v110
	v_and_b32_e32 v5, 8, v110
	v_lshlrev_b32_e32 v5, 2, v5
	v_xor_b32_e32 v4, v4, v5
	v_add3_u32 v75, v2, v3, v4
	v_lshlrev_b32_e32 v2, 12, v67
	v_add3_u32 v74, v2, v3, v4
	s_waitcnt lgkmcnt(0)
	v_mov_b32_e32 v2, 0
	v_mov_b32_e32 v3, v2
	v_mov_b32_e32 v4, v2
	v_mov_b32_e32 v5, v2
	v_mov_b32_e32 v6, v2
	v_mov_b32_e32 v7, v2
	v_mov_b32_e32 v8, v2
	v_mov_b32_e32 v9, v2
	v_mov_b32_e32 v10, v2
	v_mov_b32_e32 v11, v2
	v_mov_b32_e32 v12, v2
	v_mov_b32_e32 v13, v2
	v_mov_b32_e32 v14, v2
	v_mov_b32_e32 v15, v2
	v_mov_b32_e32 v16, v2
	v_mov_b32_e32 v17, v2
	v_mov_b32_e32 v18, v2
	v_mov_b32_e32 v19, v2
	v_mov_b32_e32 v20, v2
	v_mov_b32_e32 v21, v2
	v_mov_b32_e32 v22, v2
	v_mov_b32_e32 v23, v2
	v_mov_b32_e32 v24, v2
	v_mov_b32_e32 v25, v2
	v_mov_b32_e32 v26, v2
	v_mov_b32_e32 v27, v2
	v_mov_b32_e32 v28, v2
	v_mov_b32_e32 v29, v2
	v_mov_b32_e32 v30, v2
	v_mov_b32_e32 v31, v2
	v_mov_b32_e32 v32, v2
	v_mov_b32_e32 v33, v2
	v_mov_b32_e32 v34, v2
	v_mov_b32_e32 v35, v2
	v_mov_b32_e32 v36, v2
	v_mov_b32_e32 v37, v2
	v_mov_b32_e32 v38, v2
	v_mov_b32_e32 v39, v2
	v_mov_b32_e32 v40, v2
	v_mov_b32_e32 v41, v2
	v_mov_b32_e32 v42, v2
	v_mov_b32_e32 v43, v2
	v_mov_b32_e32 v44, v2
	v_mov_b32_e32 v45, v2
	v_mov_b32_e32 v46, v2
	v_mov_b32_e32 v47, v2
	v_mov_b32_e32 v48, v2
	v_mov_b32_e32 v49, v2
	v_mov_b32_e32 v50, v2
	v_mov_b32_e32 v51, v2
	v_mov_b32_e32 v52, v2
	v_mov_b32_e32 v53, v2
	v_mov_b32_e32 v54, v2
	v_mov_b32_e32 v55, v2
	v_mov_b32_e32 v56, v2
	v_mov_b32_e32 v57, v2
	v_mov_b32_e32 v58, v2
	v_mov_b32_e32 v59, v2
	v_mov_b32_e32 v60, v2
	v_mov_b32_e32 v61, v2
	v_mov_b32_e32 v62, v2
	v_mov_b32_e32 v63, v2
	v_mov_b32_e32 v64, v2
	v_mov_b32_e32 v65, v2
	s_mov_b64 s[18:19], 0x6ae4100
	s_mov_b64 s[40:41], 0x6aec100
	s_mov_b32 s36, 0
	s_mov_b32 s0, 0
	v_add_u32_e32 v88, s0, v75
	v_add_u32_e32 v104, s0, v74
	s_branch .Lein_head

; __device__ __forceinline__ int opaque_tid() { int t = threadIdx.x; asm volatile("" : "+v"(t)); return t; }
; #define G3_TILE(kt_, st_) do { const size_t ko_ = (size_t)(kt_) * 1024; unsigned char* d_ = smem + (st_) * 20480; \
;         _Pragma("unroll") for (int s_ = 0; s_ < 12; ++s_) GLDS16(Abase + (size_t)s_ * ksub + ko_ + voff, d_ + s_ * 1024); \
;         _Pragma("unroll") for (int s_ = 0; s_ < 8; ++s_) GLDS16(Bbase + (size_t)s_ * ksub + ko_ + voff, d_ + 12288 + s_ * 1024); } while (0)
; template <int EPI>
; __device__ __forceinline__ void gemm_tile3(const Params& p, int l, const u16* __restrict__ A, int lda, const u16* __restrict__ Bt, int K, int m0, int n0, unsigned char* smem) {
;     const int tid = opaque_tid(), lane = tid & 63, wid = tid >> 6, wr = wid >> 1, wc = wid & 1, fr = lane & 15, fq = lane >> 4;
;     f32x4 acc[6][4];
; #pragma unroll
;     for (int i = 0; i < 6; ++i)
; #pragma unroll
;         for (int j = 0; j < 4; ++j) acc[i][j] = (f32x4){0.f, 0.f, 0.f, 0.f};
;     const unsigned voff = (unsigned)(lane * 16);
;     const size_t ksub = (size_t)(K >> 5) * 1024;
;     const unsigned char* Abase = (const unsigned char*)A + (size_t)(m0 >> 4) * ksub;
;     const unsigned char* Bbase = (const unsigned char*)Bt + (size_t)(n0 >> 4) * ksub;
;     (void)lda;
;     ...
;     const int nk = K >> 5;
;     if (wid < 3) G3_TILE(wid, wid);
;     const unsigned char* fa = smem + (wr * 6) * 1024 + fr * 64 + fq * 16;
;     const unsigned char* fb = smem + 12288 + (wc * 4) * 1024 + fr * 64 + fq * 16;
;     int st = 0, stn = 3;
;     if (wid == 0) asm volatile("s_waitcnt vmcnt(0)" ::: "memory");
;     asm volatile("s_waitcnt lgkmcnt(0)" ::: "memory");
;     __builtin_amdgcn_s_barrier();
;     asm volatile("" ::: "memory");
.Lf1_pro:
	s_add_i32 s17, s51, s54
	s_add_i32 s18, s51, s0
	s_mov_b32 m0, s17
	s_add_i32 s17, s17, 0x400
	global_load_lds_dwordx4 v252, s[28:29]
	s_mov_b32 m0, s17
	s_add_i32 s17, s17, 0x400
	global_load_lds_dwordx4 v253, s[28:29]
	s_mov_b32 m0, s17
	s_nop 0
	global_load_lds_dwordx4 v254, s[28:29]
	s_mov_b32 m0, s18
	s_add_i32 s18, s18, 0x400
	global_load_lds_dwordx4 v252, s[30:31]
	s_mov_b32 m0, s18
	s_add_u32 s28, s28, 0x400
	global_load_lds_dwordx4 v253, s[30:31]
	s_addc_u32 s29, s29, 0
	s_add_u32 s30, s30, 0x400
	s_addc_u32 s31, s31, 0
	s_add_i32 s51, s51, 0x5000
	s_cmp_lg_u32 s51, 0xf000
	s_cbranch_scc1 .Lf1_pro
	v_ashrrev_i32_e32 v99, 7, v106
	s_movk_i32 s17, 0x1800
	v_and_b32_e32 v103, 15, v106
	v_mul_lo_u32 v2, v99, s17
	v_and_b32_e32 v107, 1, v98
	v_lshlrev_b32_e32 v102, 6, v103
	v_and_b32_e32 v3, 48, v106
	v_and_b32_e32 v4, 8, v106
	v_lshlrev_b32_e32 v4, 2, v4
	v_xor_b32_e32 v3, v3, v4
	v_add3_u32 v108, v2, v102, v3
	v_lshlrev_b32_e32 v2, 12, v107
	v_add3_u32 v109, v2, v102, v3
	s_waitcnt lgkmcnt(0)
	v_mov_b32_e32 v2, 0
	v_mov_b32_e32 v3, v2
	v_mov_b32_e32 v4, v2
	v_mov_b32_e32 v5, v2
	v_mov_b32_e32 v6, v2
	v_mov_b32_e32 v7, v2
	v_mov_b32_e32 v8, v2
	v_mov_b32_e32 v9, v2
	v_mov_b32_e32 v10, v2
	v_mov_b32_e32 v11, v2
	v_mov_b32_e32 v12, v2
	v_mov_b32_e32 v13, v2
	v_mov_b32_e32 v14, v2
	v_mov_b32_e32 v15, v2
	v_mov_b32_e32 v16, v2
	v_mov_b32_e32 v17, v2
	v_mov_b32_e32 v22, v2
	v_mov_b32_e32 v23, v2
	v_mov_b32_e32 v24, v2
	v_mov_b32_e32 v25, v2
	v_mov_b32_e32 v18, v2
	v_mov_b32_e32 v19, v2
	v_mov_b32_e32 v20, v2
	v_mov_b32_e32 v21, v2
	v_mov_b32_e32 v26, v2
	v_mov_b32_e32 v27, v2
	v_mov_b32_e32 v28, v2
	v_mov_b32_e32 v29, v2
	v_mov_b32_e32 v30, v2
	v_mov_b32_e32 v31, v2
	v_mov_b32_e32 v32, v2
	v_mov_b32_e32 v33, v2
	v_mov_b32_e32 v38, v2
	v_mov_b32_e32 v39, v2
	v_mov_b32_e32 v40, v2
	v_mov_b32_e32 v41, v2
	v_mov_b32_e32 v34, v2
	v_mov_b32_e32 v35, v2
	v_mov_b32_e32 v36, v2
	v_mov_b32_e32 v37, v2
	v_mov_b32_e32 v42, v2
	v_mov_b32_e32 v43, v2
	v_mov_b32_e32 v44, v2
	v_mov_b32_e32 v45, v2
	v_mov_b32_e32 v46, v2
	v_mov_b32_e32 v47, v2
	v_mov_b32_e32 v48, v2
	v_mov_b32_e32 v49, v2
	v_mov_b32_e32 v54, v2
	v_mov_b32_e32 v55, v2
	v_mov_b32_e32 v56, v2
	v_mov_b32_e32 v57, v2
	v_mov_b32_e32 v50, v2
	v_mov_b32_e32 v51, v2
	v_mov_b32_e32 v52, v2
	v_mov_b32_e32 v53, v2
	v_mov_b32_e32 v58, v2
	v_mov_b32_e32 v59, v2
	v_mov_b32_e32 v60, v2
	v_mov_b32_e32 v61, v2
	v_mov_b32_e32 v62, v2
	v_mov_b32_e32 v63, v2
	v_mov_b32_e32 v64, v2
	v_mov_b32_e32 v65, v2
	v_mov_b32_e32 v70, v2
	v_mov_b32_e32 v71, v2
	v_mov_b32_e32 v72, v2
	v_mov_b32_e32 v73, v2
	v_mov_b32_e32 v66, v2
	v_mov_b32_e32 v67, v2
	v_mov_b32_e32 v68, v2
	v_mov_b32_e32 v69, v2
	v_mov_b32_e32 v74, v2
	v_mov_b32_e32 v75, v2
	v_mov_b32_e32 v76, v2
	v_mov_b32_e32 v77, v2
	v_mov_b32_e32 v78, v2
	v_mov_b32_e32 v79, v2
	v_mov_b32_e32 v80, v2
	v_mov_b32_e32 v81, v2
	v_mov_b32_e32 v82, v2
	v_mov_b32_e32 v83, v2
	v_mov_b32_e32 v84, v2
	v_mov_b32_e32 v85, v2
	v_mov_b32_e32 v86, v2
	v_mov_b32_e32 v87, v2
	v_mov_b32_e32 v88, v2
	v_mov_b32_e32 v89, v2
	v_mov_b32_e32 v90, v2
	v_mov_b32_e32 v91, v2
	v_mov_b32_e32 v92, v2
	v_mov_b32_e32 v93, v2
	v_mov_b32_e32 v94, v2
	v_mov_b32_e32 v95, v2
	v_mov_b32_e32 v96, v2
	v_mov_b32_e32 v97, v2
	s_mov_b32 s16, 0
	s_mov_b32 s50, 0
	v_add_u32_e32 v110, s50, v109
	v_add_u32_e32 v122, 0x3000, v110
	v_add_u32_e32 v0, s50, v108
	s_branch .Lf1_head

; template <int EPI>
; __device__ __forceinline__ void gemm_tile3(const Params& p, int l, const u16* __restrict__ A, int lda, const u16* __restrict__ Bt, int K, int m0, int n0, unsigned char* smem) {
;     ...
;     for (int kt = 0; kt < nk; ++kt) {
;         if (((kt + 1) & 3) == wid && kt + 1 < nk) asm volatile("s_waitcnt vmcnt(0)" ::: "memory");
;         __builtin_amdgcn_s_barrier();
;         asm volatile("" ::: "memory");
;         if (((kt + 3) & 3) == wid && kt + 3 < nk) G3_TILE(kt + 3, stn);
;         const int so = st * 20480;
;         bf16x8 af[6], bv[4];
;         {
;             typedef __attribute__((address_space(3))) unsigned char lds_u8;
;             const unsigned la = (unsigned)(uintptr_t)(lds_u8*)(fa + so);
;             const unsigned lb = (unsigned)(uintptr_t)(lds_u8*)(fb + so);
;     ...
;             DSR128(bv[0], lb, 0); DSR128(bv[1], lb, 1024); DSR128(bv[2], lb, 2048); DSR128(bv[3], lb, 3072);
;             DSR128(af[0], la, 0); DSR128(af[1], la, 1024); DSR128(af[2], la, 2048); DSR128(af[3], la, 3072); DSR128(af[4], la, 4096); DSR128(af[5], la, 5120);
;         }
;         __builtin_amdgcn_sched_barrier(0);
;         asm volatile("s_waitcnt lgkmcnt(5)" : "+v"(bv[0]), "+v"(bv[1]), "+v"(bv[2]), "+v"(bv[3]), "+v"(af[0]));
;         __builtin_amdgcn_sched_barrier(0);
; #pragma unroll
;         for (int j = 0; j < 4; ++j) acc[0][j] = __builtin_amdgcn_mfma_f32_16x16x32_bf16(bv[j], af[0], acc[0][j], 0, 0, 0);
;         __builtin_amdgcn_sched_barrier(0);
;         asm volatile("s_waitcnt lgkmcnt(4)" : "+v"(af[1]));
;         __builtin_amdgcn_sched_barrier(0);
; #pragma unroll
;         for (int j = 0; j < 4; ++j) acc[1][j] = __builtin_amdgcn_mfma_f32_16x16x32_bf16(bv[j], af[1], acc[1][j], 0, 0, 0);
;         __builtin_amdgcn_sched_barrier(0);
;         asm volatile("s_waitcnt lgkmcnt(3)" : "+v"(af[2]));
;         __builtin_amdgcn_sched_barrier(0);
; #pragma unroll
;         for (int j = 0; j < 4; ++j) acc[2][j] = __builtin_amdgcn_mfma_f32_16x16x32_bf16(bv[j], af[2], acc[2][j], 0, 0, 0);
;         __builtin_amdgcn_sched_barrier(0);
;         asm volatile("s_waitcnt lgkmcnt(2)" : "+v"(af[3]));
;         __builtin_amdgcn_sched_barrier(0);
; #pragma unroll
;         for (int j = 0; j < 4; ++j) acc[3][j] = __builtin_amdgcn_mfma_f32_16x16x32_bf16(bv[j], af[3], acc[3][j], 0, 0, 0);
;         __builtin_amdgcn_sched_barrier(0);
.Lf1_bar:
	s_barrier
	ds_read_b128 v[110:113], v122 offset:0
	ds_read_b128 v[114:117], v122 offset:1024
	ds_read_b128 v[118:121], v122 offset:2048
	ds_read_b128 v[122:125], v122 offset:3072
	ds_read_b128 v[126:129], v0 offset:0
	ds_read_b128 v[130:133], v0 offset:1024
	ds_read_b128 v[134:137], v0 offset:2048
	ds_read_b128 v[138:141], v0 offset:3072
	ds_read_b128 v[142:145], v0 offset:4096
	ds_read_b128 v[146:149], v0 offset:5120
	s_cmp_lt_u32 s16, 29
	s_cbranch_scc0 .Lf1_mm
	s_add_i32 s17, s51, s54
	s_add_i32 s18, s51, s0
	s_mov_b32 m0, s17
	s_add_i32 s17, s17, 0x400
	global_load_lds_dwordx4 v252, s[28:29]
	s_mov_b32 m0, s17
	s_add_i32 s17, s17, 0x400
	global_load_lds_dwordx4 v253, s[28:29]
	s_mov_b32 m0, s17
	s_nop 0
	global_load_lds_dwordx4 v254, s[28:29]
	s_mov_b32 m0, s18
	s_add_i32 s18, s18, 0x400
	global_load_lds_dwordx4 v252, s[30:31]
	s_mov_b32 m0, s18
	s_add_u32 s28, s28, 0x400
	global_load_lds_dwordx4 v253, s[30:31]
	s_addc_u32 s29, s29, 0
	s_add_u32 s30, s30, 0x400
	s_addc_u32 s31, s31, 0
	s_add_i32 s51, s51, 0x5000
	s_cmp_eq_u32 s51, 0x14000
	s_cselect_b32 s51, 0, s51
.Lf1_mm:
	s_setprio 1
	s_waitcnt lgkmcnt(5)
	s_nop 0
	v_mfma_f32_16x16x32_bf16 v[94:97], v[110:113], v[126:129], v[94:97]
	v_mfma_f32_16x16x32_bf16 v[90:93], v[114:117], v[126:129], v[90:93]
	v_mfma_f32_16x16x32_bf16 v[86:89], v[118:121], v[126:129], v[86:89]
	v_mfma_f32_16x16x32_bf16 v[82:85], v[122:125], v[126:129], v[82:85]
	s_waitcnt lgkmcnt(4)
	s_nop 0
	v_mfma_f32_16x16x32_bf16 v[78:81], v[110:113], v[130:133], v[78:81]
	v_mfma_f32_16x16x32_bf16 v[74:77], v[114:117], v[130:133], v[74:77]
	v_mfma_f32_16x16x32_bf16 v[66:69], v[118:121], v[130:133], v[66:69]
	v_mfma_f32_16x16x32_bf16 v[70:73], v[122:125], v[130:133], v[70:73]
	s_waitcnt lgkmcnt(3)
	s_nop 0
	v_mfma_f32_16x16x32_bf16 v[62:65], v[110:113], v[134:137], v[62:65]
	v_mfma_f32_16x16x32_bf16 v[58:61], v[114:117], v[134:137], v[58:61]
	v_mfma_f32_16x16x32_bf16 v[50:53], v[118:121], v[134:137], v[50:53]
	v_mfma_f32_16x16x32_bf16 v[54:57], v[122:125], v[134:137], v[54:57]
	s_waitcnt lgkmcnt(2)
	s_nop 0
	v_mfma_f32_16x16x32_bf16 v[46:49], v[110:113], v[138:141], v[46:49]
	v_mfma_f32_16x16x32_bf16 v[42:45], v[114:117], v[138:141], v[42:45]
	v_mfma_f32_16x16x32_bf16 v[34:37], v[118:121], v[138:141], v[34:37]
	v_mfma_f32_16x16x32_bf16 v[38:41], v[122:125], v[138:141], v[38:41]
	s_waitcnt lgkmcnt(1)
	s_nop 0
	v_mfma_f32_16x16x32_bf16 v[30:33], v[110:113], v[142:145], v[30:33]
	v_mfma_f32_16x16x32_bf16 v[26:29], v[114:117], v[142:145], v[26:29]
	v_mfma_f32_16x16x32_bf16 v[18:21], v[118:121], v[142:145], v[18:21]
	v_mfma_f32_16x16x32_bf16 v[22:25], v[122:125], v[142:145], v[22:25]
	s_waitcnt lgkmcnt(0)
	s_add_i32 s50, s50, 0x5000
	s_add_i32 s16, s16, 1
	v_mfma_f32_16x16x32_bf16 v[14:17], v[110:113], v[146:149], v[14:17]
	s_cmp_eq_u32 s50, 0x14000
	s_cselect_b32 s50, 0, s50
	v_mfma_f32_16x16x32_bf16 v[10:13], v[114:117], v[146:149], v[10:13]
	s_cmp_lg_u32 s16, 31
	v_mfma_f32_16x16x32_bf16 v[6:9], v[118:121], v[146:149], v[6:9]
	v_mfma_f32_16x16x32_bf16 v[2:5], v[122:125], v[146:149], v[2:5]
	v_add_u32_e32 v110, s50, v109
	v_add_u32_e32 v122, 0x3000, v110
	v_add_u32_e32 v0, s50, v108
	s_setprio 0
	s_cbranch_scc1 .Lf1_head
	s_branch .LBB0_892

; __device__ __forceinline__ int opaque_tid() { int t = threadIdx.x; asm volatile("" : "+v"(t)); return t; }
; #define G3_TILE(kt_, st_) do { const size_t ko_ = (size_t)(kt_) * 1024; unsigned char* d_ = smem + (st_) * 20480; \
;         _Pragma("unroll") for (int s_ = 0; s_ < 12; ++s_) GLDS16(Abase + (size_t)s_ * ksub + ko_ + voff, d_ + s_ * 1024); \
;         _Pragma("unroll") for (int s_ = 0; s_ < 8; ++s_) GLDS16(Bbase + (size_t)s_ * ksub + ko_ + voff, d_ + 12288 + s_ * 1024); } while (0)
; template <int EPI>
; __device__ __forceinline__ void gemm_tile3(const Params& p, int l, const u16* __restrict__ A, int lda, const u16* __restrict__ Bt, int K, int m0, int n0, unsigned char* smem) {
;     const int tid = opaque_tid(), lane = tid & 63, wid = tid >> 6, wr = wid >> 1, wc = wid & 1, fr = lane & 15, fq = lane >> 4;
;     f32x4 acc[6][4];
; #pragma unroll
;     for (int i = 0; i < 6; ++i)
; #pragma unroll
;         for (int j = 0; j < 4; ++j) acc[i][j] = (f32x4){0.f, 0.f, 0.f, 0.f};
;     const unsigned voff = (unsigned)(lane * 16);
;     const size_t ksub = (size_t)(K >> 5) * 1024;
;     const unsigned char* Abase = (const unsigned char*)A + (size_t)(m0 >> 4) * ksub;
;     const unsigned char* Bbase = (const unsigned char*)Bt + (size_t)(n0 >> 4) * ksub;
;     (void)lda;
;     ...
;     const int nk = K >> 5;
;     if (wid < 3) G3_TILE(wid, wid);
;     const unsigned char* fa = smem + (wr * 6) * 1024 + fr * 64 + fq * 16;
;     const unsigned char* fb = smem + 12288 + (wc * 4) * 1024 + fr * 64 + fq * 16;
;     int st = 0, stn = 3;
;     if (wid == 0) asm volatile("s_waitcnt vmcnt(0)" ::: "memory");
;     asm volatile("s_waitcnt lgkmcnt(0)" ::: "memory");
;     __builtin_amdgcn_s_barrier();
;     asm volatile("" ::: "memory");
.Lf2_pro:
	s_add_i32 s17, s23, s54
	s_add_i32 s18, s23, s55
	s_mov_b32 m0, s17
	s_add_i32 s17, s17, 0x400
	global_load_lds_dwordx4 v252, s[28:29]
	s_mov_b32 m0, s17
	s_add_i32 s17, s17, 0x400
	global_load_lds_dwordx4 v253, s[28:29]
	s_mov_b32 m0, s17
	s_nop 0
	global_load_lds_dwordx4 v254, s[28:29]
	s_mov_b32 m0, s18
	s_add_i32 s18, s18, 0x400
	global_load_lds_dwordx4 v252, s[30:31]
	s_mov_b32 m0, s18
	s_add_u32 s28, s28, 0x400
	global_load_lds_dwordx4 v253, s[30:31]
	s_addc_u32 s29, s29, 0
	s_add_u32 s30, s30, 0x400
	s_addc_u32 s31, s31, 0
	s_add_i32 s23, s23, 0x5000
	s_cmp_lg_u32 s23, 0xf000
	s_cbranch_scc1 .Lf2_pro
	v_ashrrev_i32_e32 v105, 7, v104
	s_movk_i32 s17, 0x1800
	v_and_b32_e32 v106, 15, v104
	v_mul_lo_u32 v2, v105, s17
	v_and_b32_e32 v99, 1, v98
	v_lshlrev_b32_e32 v3, 6, v106
	v_and_b32_e32 v4, 48, v104
	v_and_b32_e32 v5, 8, v104
	v_lshlrev_b32_e32 v5, 2, v5
	v_xor_b32_e32 v4, v4, v5
	v_add3_u32 v107, v2, v3, v4
	v_lshlrev_b32_e32 v2, 12, v99
	v_add3_u32 v108, v2, v3, v4
	s_waitcnt lgkmcnt(0)
	v_mov_b32_e32 v2, 0
	v_mov_b32_e32 v3, v2
	v_mov_b32_e32 v4, v2
	v_mov_b32_e32 v5, v2
	v_mov_b32_e32 v6, v2
	v_mov_b32_e32 v7, v2
	v_mov_b32_e32 v8, v2
	v_mov_b32_e32 v9, v2
	v_mov_b32_e32 v10, v2
	v_mov_b32_e32 v11, v2
	v_mov_b32_e32 v12, v2
	v_mov_b32_e32 v13, v2
	v_mov_b32_e32 v14, v2
	v_mov_b32_e32 v15, v2
	v_mov_b32_e32 v16, v2
	v_mov_b32_e32 v17, v2
	v_mov_b32_e32 v18, v2
	v_mov_b32_e32 v19, v2
	v_mov_b32_e32 v20, v2
	v_mov_b32_e32 v21, v2
	v_mov_b32_e32 v22, v2
	v_mov_b32_e32 v23, v2
	v_mov_b32_e32 v24, v2
	v_mov_b32_e32 v25, v2
	v_mov_b32_e32 v26, v2
	v_mov_b32_e32 v27, v2
	v_mov_b32_e32 v28, v2
	v_mov_b32_e32 v29, v2
	v_mov_b32_e32 v30, v2
	v_mov_b32_e32 v31, v2
	v_mov_b32_e32 v32, v2
	v_mov_b32_e32 v33, v2
	v_mov_b32_e32 v34, v2
	v_mov_b32_e32 v35, v2
	v_mov_b32_e32 v36, v2
	v_mov_b32_e32 v37, v2
	v_mov_b32_e32 v38, v2
	v_mov_b32_e32 v39, v2
	v_mov_b32_e32 v40, v2
	v_mov_b32_e32 v41, v2
	v_mov_b32_e32 v42, v2
	v_mov_b32_e32 v43, v2
	v_mov_b32_e32 v44, v2
	v_mov_b32_e32 v45, v2
	v_mov_b32_e32 v46, v2
	v_mov_b32_e32 v47, v2
	v_mov_b32_e32 v48, v2
	v_mov_b32_e32 v49, v2
	v_mov_b32_e32 v50, v2
	v_mov_b32_e32 v51, v2
	v_mov_b32_e32 v52, v2
	v_mov_b32_e32 v53, v2
	v_mov_b32_e32 v54, v2
	v_mov_b32_e32 v55, v2
	v_mov_b32_e32 v56, v2
	v_mov_b32_e32 v57, v2
	v_mov_b32_e32 v58, v2
	v_mov_b32_e32 v59, v2
	v_mov_b32_e32 v60, v2
	v_mov_b32_e32 v61, v2
	v_mov_b32_e32 v62, v2
	v_mov_b32_e32 v63, v2
	v_mov_b32_e32 v64, v2
	v_mov_b32_e32 v65, v2
	v_mov_b32_e32 v66, v2
	v_mov_b32_e32 v67, v2
	v_mov_b32_e32 v68, v2
	v_mov_b32_e32 v69, v2
	v_mov_b32_e32 v70, v2
	v_mov_b32_e32 v71, v2
	v_mov_b32_e32 v72, v2
	v_mov_b32_e32 v73, v2
	v_mov_b32_e32 v74, v2
	v_mov_b32_e32 v75, v2
	v_mov_b32_e32 v76, v2
	v_mov_b32_e32 v77, v2
	v_mov_b32_e32 v78, v2
	v_mov_b32_e32 v79, v2
	v_mov_b32_e32 v80, v2
	v_mov_b32_e32 v81, v2
	v_mov_b32_e32 v82, v2
	v_mov_b32_e32 v83, v2
	v_mov_b32_e32 v84, v2
	v_mov_b32_e32 v85, v2
	v_mov_b32_e32 v86, v2
	v_mov_b32_e32 v87, v2
	v_mov_b32_e32 v88, v2
	v_mov_b32_e32 v89, v2
	v_mov_b32_e32 v90, v2
	v_mov_b32_e32 v91, v2
	v_mov_b32_e32 v92, v2
	v_mov_b32_e32 v93, v2
	v_mov_b32_e32 v94, v2
	v_mov_b32_e32 v95, v2
	v_mov_b32_e32 v96, v2
	v_mov_b32_e32 v97, v2
	s_mov_b32 s50, 0
	s_mov_b32 s41, 0
	v_add_u32_e32 v109, s41, v108
	v_add_u32_e32 v0, s41, v107
	v_add_u32_e32 v109, 0x3000, v109
	s_branch .Lf2_head

; template <int EPI>
; __device__ __forceinline__ void gemm_tile3(const Params& p, int l, const u16* __restrict__ A, int lda, const u16* __restrict__ Bt, int K, int m0, int n0, unsigned char* smem) {
;     ...
;     for (int kt = 0; kt < nk; ++kt) {
;         if (((kt + 1) & 3) == wid && kt + 1 < nk) asm volatile("s_waitcnt vmcnt(0)" ::: "memory");
;         __builtin_amdgcn_s_barrier();
;         asm volatile("" ::: "memory");
;         if (((kt + 3) & 3) == wid && kt + 3 < nk) G3_TILE(kt + 3, stn);
;         const int so = st * 20480;
;         bf16x8 af[6], bv[4];
;         {
;             typedef __attribute__((address_space(3))) unsigned char lds_u8;
;             const unsigned la = (unsigned)(uintptr_t)(lds_u8*)(fa + so);
;             const unsigned lb = (unsigned)(uintptr_t)(lds_u8*)(fb + so);
;     ...
;             DSR128(bv[0], lb, 0); DSR128(bv[1], lb, 1024); DSR128(bv[2], lb, 2048); DSR128(bv[3], lb, 3072);
;             DSR128(af[0], la, 0); DSR128(af[1], la, 1024); DSR128(af[2], la, 2048); DSR128(af[3], la, 3072); DSR128(af[4], la, 4096); DSR128(af[5], la, 5120);
;         }
;         __builtin_amdgcn_sched_barrier(0);
;         asm volatile("s_waitcnt lgkmcnt(5)" : "+v"(bv[0]), "+v"(bv[1]), "+v"(bv[2]), "+v"(bv[3]), "+v"(af[0]));
;         __builtin_amdgcn_sched_barrier(0);
; #pragma unroll
;         for (int j = 0; j < 4; ++j) acc[0][j] = __builtin_amdgcn_mfma_f32_16x16x32_bf16(bv[j], af[0], acc[0][j], 0, 0, 0);
;         __builtin_amdgcn_sched_barrier(0);
;         asm volatile("s_waitcnt lgkmcnt(4)" : "+v"(af[1]));
;         __builtin_amdgcn_sched_barrier(0);
; #pragma unroll
;         for (int j = 0; j < 4; ++j) acc[1][j] = __builtin_amdgcn_mfma_f32_16x16x32_bf16(bv[j], af[1], acc[1][j], 0, 0, 0);
;         __builtin_amdgcn_sched_barrier(0);
;         asm volatile("s_waitcnt lgkmcnt(3)" : "+v"(af[2]));
;         __builtin_amdgcn_sched_barrier(0);
; #pragma unroll
;         for (int j = 0; j < 4; ++j) acc[2][j] = __builtin_amdgcn_mfma_f32_16x16x32_bf16(bv[j], af[2], acc[2][j], 0, 0, 0);
;         __builtin_amdgcn_sched_barrier(0);
;         asm volatile("s_waitcnt lgkmcnt(2)" : "+v"(af[3]));
;         __builtin_amdgcn_sched_barrier(0);
; #pragma unroll
;         for (int j = 0; j < 4; ++j) acc[3][j] = __builtin_amdgcn_mfma_f32_16x16x32_bf16(bv[j], af[3], acc[3][j], 0, 0, 0);
;         __builtin_amdgcn_sched_barrier(0);
.Lf2_bar:
	s_barrier
	ds_read_b128 v[110:113], v109 offset:0
	ds_read_b128 v[114:117], v109 offset:1024
	ds_read_b128 v[118:121], v109 offset:2048
	ds_read_b128 v[122:125], v109 offset:3072
	ds_read_b128 v[126:129], v0 offset:0
	ds_read_b128 v[130:133], v0 offset:1024
	ds_read_b128 v[134:137], v0 offset:2048
	ds_read_b128 v[138:141], v0 offset:3072
	ds_read_b128 v[142:145], v0 offset:4096
	ds_read_b128 v[146:149], v0 offset:5120
	s_cmp_lt_u32 s50, 85
	s_cbranch_scc0 .Lf2_mm
	s_add_i32 s17, s23, s54
	s_add_i32 s18, s23, s55
	s_mov_b32 m0, s17
	s_add_i32 s17, s17, 0x400
	global_load_lds_dwordx4 v252, s[28:29]
	s_mov_b32 m0, s17
	s_add_i32 s17, s17, 0x400
	global_load_lds_dwordx4 v253, s[28:29]
	s_mov_b32 m0, s17
	s_nop 0
	global_load_lds_dwordx4 v254, s[28:29]
	s_mov_b32 m0, s18
	s_add_i32 s18, s18, 0x400
	global_load_lds_dwordx4 v252, s[30:31]
	s_mov_b32 m0, s18
	s_add_u32 s28, s28, 0x400
	global_load_lds_dwordx4 v253, s[30:31]
	s_addc_u32 s29, s29, 0
	s_add_u32 s30, s30, 0x400
	s_addc_u32 s31, s31, 0
	s_add_i32 s23, s23, 0x5000
	s_cmp_eq_u32 s23, 0x14000
	s_cselect_b32 s23, 0, s23
.Lf2_mm:
	s_setprio 1
	s_waitcnt lgkmcnt(5)
	s_nop 0
	v_mfma_f32_16x16x32_bf16 v[94:97], v[110:113], v[126:129], v[94:97]
	v_mfma_f32_16x16x32_bf16 v[90:93], v[114:117], v[126:129], v[90:93]
	v_mfma_f32_16x16x32_bf16 v[86:89], v[118:121], v[126:129], v[86:89]
	v_mfma_f32_16x16x32_bf16 v[82:85], v[122:125], v[126:129], v[82:85]
	s_waitcnt lgkmcnt(4)
	s_nop 0
	v_mfma_f32_16x16x32_bf16 v[78:81], v[110:113], v[130:133], v[78:81]
	v_mfma_f32_16x16x32_bf16 v[74:77], v[114:117], v[130:133], v[74:77]
	v_mfma_f32_16x16x32_bf16 v[70:73], v[118:121], v[130:133], v[70:73]
	v_mfma_f32_16x16x32_bf16 v[66:69], v[122:125], v[130:133], v[66:69]
	s_waitcnt lgkmcnt(3)
	s_nop 0
	v_mfma_f32_16x16x32_bf16 v[62:65], v[110:113], v[134:137], v[62:65]
	v_mfma_f32_16x16x32_bf16 v[58:61], v[114:117], v[134:137], v[58:61]
	v_mfma_f32_16x16x32_bf16 v[54:57], v[118:121], v[134:137], v[54:57]
	v_mfma_f32_16x16x32_bf16 v[50:53], v[122:125], v[134:137], v[50:53]
	s_waitcnt lgkmcnt(2)
	s_nop 0
	v_mfma_f32_16x16x32_bf16 v[46:49], v[110:113], v[138:141], v[46:49]
	v_mfma_f32_16x16x32_bf16 v[42:45], v[114:117], v[138:141], v[42:45]
	v_mfma_f32_16x16x32_bf16 v[38:41], v[118:121], v[138:141], v[38:41]
	v_mfma_f32_16x16x32_bf16 v[34:37], v[122:125], v[138:141], v[34:37]
	s_waitcnt lgkmcnt(1)
	s_nop 0
	v_mfma_f32_16x16x32_bf16 v[30:33], v[110:113], v[142:145], v[30:33]
	v_mfma_f32_16x16x32_bf16 v[26:29], v[114:117], v[142:145], v[26:29]
	v_mfma_f32_16x16x32_bf16 v[22:25], v[118:121], v[142:145], v[22:25]
	v_mfma_f32_16x16x32_bf16 v[18:21], v[122:125], v[142:145], v[18:21]
	s_waitcnt lgkmcnt(0)
	s_add_i32 s41, s41, 0x5000
	s_add_i32 s50, s50, 1
	v_mfma_f32_16x16x32_bf16 v[14:17], v[110:113], v[146:149], v[14:17]
	s_cmp_eq_u32 s41, 0x14000
	s_cselect_b32 s41, 0, s41
	v_mfma_f32_16x16x32_bf16 v[10:13], v[114:117], v[146:149], v[10:13]
	s_cmp_lg_u32 s50, 88
	v_mfma_f32_16x16x32_bf16 v[6:9], v[118:121], v[146:149], v[6:9]
	v_mfma_f32_16x16x32_bf16 v[2:5], v[122:125], v[146:149], v[2:5]
	v_add_u32_e32 v109, s41, v108
	v_add_u32_e32 v0, s41, v107
	v_add_u32_e32 v109, 0x3000, v109
	s_setprio 0
	s_cbranch_scc1 .Lf2_head
	s_branch .LBB0_956
